# claim-ahead in the FFN-up idle conversion site on top of the XCD-split last round, 5 idle tiles
# speedup vs baseline: 1.0025x; 1.0025x over previous
; #define LAS __attribute__((address_space(3)))
; __device__ __forceinline__ unsigned pk2(float lo, float hi) { return f2bf(lo) | (f2bf(hi) << 16); }
; __device__ __forceinline__ void tr_to_lds(LAS unsigned* T, int tid, const f32x4 (&v)[8][2]) {
;     const int c4 = (tid & 15) + 16 * ((tid >> 6) & 1), rp = ((tid >> 4) & 3) + 4 * (tid >> 7);
; #pragma unroll
;     for (int i = 0; i < 8; ++i)
; #pragma unroll
;         for (int j = 0; j < 4; ++j) T[(4 * c4 + j) * 132 + 16 * i + rp] = pk2(v[i][0][j], v[i][1][j]);
; }
; __device__ __forceinline__ void tr_store(const TrJob& jb, const LAS unsigned* T, int tid, int k0, int n0) {
;     const int w = tid >> 6, lane = tid & 63, c = 8 * (w >> 1) + (lane & 7), nb = 64 * (w & 1) + (lane >> 3);
.LBB0_345:
	v_and_b32_e32 v69, -4, v71
	v_ashrrev_i32_e32 v71, 4, v2
	v_bfe_u32 v68, v2, 4, 2
	s_cmp_lg_u32 s31, 0
	v_bfi_b32 v71, -8, v71, v2
	v_lshrrev_b32_e32 v2, 3, v2
	s_cselect_b64 s[4:5], -1, 0
	v_lshlrev_b32_e32 v68, 2, v68
	v_lshlrev_b32_e32 v69, 2, v69
	v_and_or_b32 v79, v2, 7, v70
	s_cmp_lg_u64 s[4:5], 0
	v_readlane_b32 s4, v254, 63
	v_add3_u32 v68, 0, v68, v69
	v_mul_u32_u24_e32 v69, 0x210, v77
	v_lshl_add_u32 v2, v71, 4, 0
	v_mul_u32_u24_e32 v70, 0x210, v79
	s_subb_u32 s21, s4, 0
	v_lshlrev_b32_e32 v80, 3, v71
	v_or_b32_e32 v81, 8, v79
	v_or_b32_e32 v82, 16, v79
	v_or_b32_e32 v83, 24, v79
	v_or_b32_e32 v84, 32, v79
	v_or_b32_e32 v85, 40, v79
	v_or_b32_e32 v86, 48, v79
	v_or_b32_e32 v87, 56, v79
	v_add_u32_e32 v88, v68, v69
	v_add_u32_e32 v89, v2, v70
	s_mov_b32 s79, 0
	s_branch .LBB0_347

; #define LAS __attribute__((address_space(3)))
; __device__ __forceinline__ unsigned pk2(float lo, float hi) { return f2bf(lo) | (f2bf(hi) << 16); }
; __device__ __forceinline__ void tr_to_lds(LAS unsigned* T, int tid, const f32x4 (&v)[8][2]) {
;     const int c4 = (tid & 15) + 16 * ((tid >> 6) & 1), rp = ((tid >> 4) & 3) + 4 * (tid >> 7);
; #pragma unroll
;     for (int i = 0; i < 8; ++i)
; #pragma unroll
;         for (int j = 0; j < 4; ++j) T[(4 * c4 + j) * 132 + 16 * i + rp] = pk2(v[i][0][j], v[i][1][j]);
; __device__ __forceinline__ unsigned conv_claim(unsigned* ctr, volatile LAS unsigned* slot, int limit, int extra, unsigned known, bool peek) {
;     if (peek) known = __hip_atomic_load(ctr, __ATOMIC_RELAXED, __HIP_MEMORY_SCOPE_AGENT);
;     const bool need = (int)known < limit, opt = !need && extra > 0 && (int)known < TL_ALL;
;     unsigned T = 0xffffffffu;
;     if (need || opt) { T = __hip_atomic_fetch_add(ctr, 1u, __ATOMIC_RELAXED, __HIP_MEMORY_SCOPE_AGENT); known = T + 1u; if ((int)T >= TL_ALL) T = 0xffffffffu; }
;     slot[0] = T; slot[1] = need ? 0u : 1u;
.Lgm__347_15:
	v_bfe_u32 v73, v64, 16, 1
	v_lshrrev_b32_e32 v72, 16, v72
	v_add3_u32 v73, v64, v73, s81
	v_and_or_b32 v72, v73, s82, v72
	ds_write2_b32 v88, v2, v72 offset0:96 offset1:112
	v_bfe_u32 v2, v61, 16, 1
	v_add3_u32 v2, v61, v2, s81
	v_bfe_u32 v72, v65, 16, 1
	v_lshrrev_b32_e32 v2, 16, v2
	v_add3_u32 v72, v65, v72, s81
	v_and_or_b32 v2, v72, s82, v2
	ds_write2_b32 v88, v69, v2 offset0:228 offset1:244
	v_bfe_u32 v2, v62, 16, 1
	v_add3_u32 v2, v62, v2, s81
	v_bfe_u32 v69, v66, 16, 1
	v_lshrrev_b32_e32 v2, 16, v2
	v_add3_u32 v69, v66, v69, s81
	v_and_or_b32 v2, v69, s82, v2
	ds_write2_b32 v68, v70, v2 offset0:104 offset1:120
	v_bfe_u32 v2, v63, 16, 1
	v_add3_u32 v2, v63, v2, s81
	v_bfe_u32 v69, v67, 16, 1
	v_lshrrev_b32_e32 v2, 16, v2
	v_add3_u32 v69, v67, v69, s81
	s_mov_b32 s24, s15
	s_mov_b32 s30, s14
	s_mov_b64 s[6:7], s[0:1]
	s_mov_b32 s22, s19
	s_mov_b32 s25, s34
	s_mov_b32 s23, s20
	v_and_or_b32 v2, v69, s82, v2
	ds_write2_b32 v68, v71, v2 offset0:236 offset1:252
	s_and_saveexec_b64 s[4:5], s[2:3]
	s_cbranch_execz .LBB0_353
	s_cmp_lg_u32 s79, 0
	s_cbranch_scc0 .Lca347_orig
	s_mov_b32 s79, 0
	s_mov_b64 s[8:9], exec
	s_cmp_lg_u32 s65, 0
	s_cselect_b64 vcc, exec, 0
	v_mov_b32_e32 v2, 0
	s_waitcnt vmcnt(0)
	v_mov_b32_e32 v68, v142
	s_branch .Lca347_join

; #define LAS __attribute__((address_space(3)))
; __device__ __forceinline__ void tr_load(const TrJob& jb, int tile, int tid, f32x4 (&v)[8][2], int& k0, int& n0) {
;     const int nblk = (jb.N + 127) / 128, kt = tile / nblk, nt = tile - kt * nblk; k0 = 256 * kt; n0 = 128 * nt;
;     const int c4 = (tid & 15) + 16 * ((tid >> 6) & 1), rp = ((tid >> 4) & 3) + 4 * (tid >> 7);
;     int col = n0 + 4 * c4; col = col < jb.N - 4 ? col : jb.N - 4;
;     const float* wp = jb.W + (size_t)(k0 + 2 * rp) * jb.N + col;
; #pragma unroll
;     for (int i = 0; i < 8; ++i) { v[i][0] = *(const f32x4*)(wp + (size_t)(32 * i) * jb.N); v[i][1] = *(const f32x4*)(wp + (size_t)(32 * i + 1) * jb.N); }
; __device__ __forceinline__ unsigned conv_claim(unsigned* ctr, volatile LAS unsigned* slot, int limit, int extra, unsigned known, bool peek) {
;     if (peek) known = __hip_atomic_load(ctr, __ATOMIC_RELAXED, __HIP_MEMORY_SCOPE_AGENT);
;     const bool need = (int)known < limit, opt = !need && extra > 0 && (int)known < TL_ALL;
;     unsigned T = 0xffffffffu;
;     if (need || opt) { T = __hip_atomic_fetch_add(ctr, 1u, __ATOMIC_RELAXED, __HIP_MEMORY_SCOPE_AGENT); known = T + 1u; if ((int)T >= TL_ALL) T = 0xffffffffu; }
.Lgf__347_8104:
	s_mov_b32 s79, 0
	s_and_saveexec_b64 s[86:87], s[2:3]
	s_cbranch_execz .Lca347_done
	v_readfirstlane_b32 s27, v76
	s_cmp_lg_u32 s26, 0
	s_cselect_b32 s18, 1, 0
	s_sub_i32 s18, s21, s18
	s_cmp_lt_i32 s27, s59
	s_cselect_b32 s65, 1, 0
	s_cmp_gt_i32 s18, 0
	s_cselect_b32 s18, 1, 0
	s_cmpk_lt_i32 s27, 0x2fa0
	s_cselect_b32 s67, 1, 0
	s_and_b32 s18, s18, s67
	s_or_b32 s18, s18, s65
	s_cmp_lg_u32 s18, 0
	s_cbranch_scc0 .Lca347_done
	v_mov_b32_e32 v143, 1
	v_readlane_b32 s98, v252, 39
	v_readlane_b32 s99, v252, 40
	s_mov_b32 s79, 1
	s_nop 4
	global_atomic_add v142, v3, v143, s[98:99] sc0
.Lca347_done:
	s_or_b64 exec, exec, s[86:87]
	global_load_dwordx4 v[4:7], v[4:5], off sc1 nt
	s_nop 0
	global_load_dwordx4 v[8:11], v[12:13], off sc1 nt
	v_lshl_add_u64 v[12:13], v[12:13], 0, s[12:13]
	v_lshl_add_u64 v[20:21], v[12:13], 0, s[10:11]
	global_load_dwordx4 v[12:15], v[12:13], off sc1 nt
	s_nop 0
	global_load_dwordx4 v[16:19], v[20:21], off sc1 nt
	v_lshl_add_u64 v[20:21], v[20:21], 0, s[12:13]
	v_lshl_add_u64 v[28:29], v[20:21], 0, s[10:11]
	global_load_dwordx4 v[20:23], v[20:21], off sc1 nt
	s_nop 0
	global_load_dwordx4 v[24:27], v[28:29], off sc1 nt
	v_lshl_add_u64 v[28:29], v[28:29], 0, s[12:13]
	v_lshl_add_u64 v[36:37], v[28:29], 0, s[10:11]
	v_lshl_add_u64 v[40:41], v[36:37], 0, s[12:13]
	v_lshl_add_u64 v[44:45], v[40:41], 0, s[10:11]
	v_lshl_add_u64 v[48:49], v[44:45], 0, s[12:13]
	v_lshl_add_u64 v[52:53], v[48:49], 0, s[10:11]
	v_lshl_add_u64 v[56:57], v[52:53], 0, s[12:13]
	v_lshl_add_u64 v[60:61], v[56:57], 0, s[10:11]
	v_lshl_add_u64 v[64:65], v[60:61], 0, s[12:13]
	global_load_dwordx4 v[28:31], v[28:29], off sc1 nt
	s_nop 0
	global_load_dwordx4 v[32:35], v[36:37], off sc1 nt
	s_cmp_eq_u64 s[8:9], 0
	global_load_dwordx4 v[36:39], v[40:41], off sc1 nt
	s_nop 0
	global_load_dwordx4 v[40:43], v[44:45], off sc1 nt
	s_nop 0
	global_load_dwordx4 v[44:47], v[48:49], off sc1 nt
	s_nop 0
	global_load_dwordx4 v[48:51], v[52:53], off sc1 nt
	s_nop 0
	global_load_dwordx4 v[52:55], v[56:57], off sc1 nt
	s_nop 0
	global_load_dwordx4 v[56:59], v[60:61], off sc1 nt
	s_nop 0
	global_load_dwordx4 v[60:63], v[64:65], off sc1 nt
	v_lshl_add_u64 v[64:65], v[64:65], 0, s[10:11]
	global_load_dwordx4 v[64:67], v[64:65], off sc1 nt
